# speedup vs baseline: 1.0070x; 1.0070x over previous
;     ...
;     __syncthreads();
; #pragma unroll
;     for (int i = 0; i < 8; ++i) {
;       const int id = tid + i * 512;
;       const int r = id >> 6, c4 = (id & 63) * 4;
;       tile[r * 257 + c4 + 0] = v[i][0];
;       tile[r * 257 + c4 + 1] = v[i][1];
;       tile[r * 257 + c4 + 2] = v[i][2];
;       tile[r * 257 + c4 + 3] = v[i][3];
;     }
;     __syncthreads();
; #pragma unroll
;     for (int i = 0; i < 4; ++i) {
;       const int id = tid + i * 512;
;       const int n = id >> 3, kc = id & 7;
;       uint4 o;
;       o.x = pack2(tile[(kc * 8 + 0) * 257 + n], tile[(kc * 8 + 1) * 257 + n]);
;       o.y = pack2(tile[(kc * 8 + 2) * 257 + n], tile[(kc * 8 + 3) * 257 + n]);
;       o.z = pack2(tile[(kc * 8 + 4) * 257 + n], tile[(kc * 8 + 5) * 257 + n]);
;       o.w = pack2(tile[(kc * 8 + 6) * 257 + n], tile[(kc * 8 + 7) * 257 + n]);
;       *(uint4*)(dst + (size_t)(n0 + n) * K + k0 + kc * 8) = o;
;     }
.LBB0_29:
	s_or_b64 exec, exec, s[46:47]
	s_barrier
	s_waitcnt vmcnt(7)
	ds_write2_b32 v57, v6, v7 offset1:1
	ds_write2_b32 v57, v8, v9 offset0:2 offset1:3
	s_waitcnt vmcnt(6)
	ds_write2_b32 v58, v2, v3 offset1:1
	ds_write2_b32 v58, v4, v5 offset0:2 offset1:3
	s_waitcnt vmcnt(5)
	ds_write2_b32 v59, v14, v15 offset1:1
	ds_write2_b32 v59, v16, v17 offset0:2 offset1:3
	s_waitcnt vmcnt(4)
	ds_write2_b32 v60, v10, v11 offset1:1
	ds_write2_b32 v60, v12, v13 offset0:2 offset1:3
	s_waitcnt vmcnt(3)
	ds_write2_b32 v61, v22, v23 offset1:1
	ds_write2_b32 v61, v24, v25 offset0:2 offset1:3
	s_waitcnt vmcnt(2)
	ds_write2_b32 v62, v18, v19 offset1:1
	ds_write2_b32 v62, v20, v21 offset0:2 offset1:3
	s_waitcnt vmcnt(1)
	ds_write2_b32 v63, v30, v31 offset1:1
	ds_write2_b32 v63, v32, v33 offset0:2 offset1:3
	s_waitcnt vmcnt(0)
	ds_write2_b32 v64, v26, v27 offset1:1
	ds_write2_b32 v64, v28, v29 offset0:2 offset1:3
	s_waitcnt lgkmcnt(0)
	s_barrier
	ds_read_b32 v2, v42
	ds_read_b32 v3, v42 offset:1028
	ds_read_b32 v4, v42 offset:2056
	ds_read_b32 v5, v42 offset:3084
	ds_read_b32 v8, v42 offset:4112
	ds_read_b32 v9, v42 offset:5140
	ds_read_b32 v10, v42 offset:6168
	ds_read_b32 v11, v42 offset:7196
	s_sub_i32 s46, 0, s45
	s_add_i32 s46, s46, s48
	s_waitcnt lgkmcnt(6)
	v_cvt_pk_bf16_f32 v2, v2, v3
	s_waitcnt lgkmcnt(4)
	v_cvt_pk_bf16_f32 v3, v4, v5
	s_waitcnt lgkmcnt(2)
	v_cvt_pk_bf16_f32 v4, v8, v9
	s_waitcnt lgkmcnt(0)
	v_cvt_pk_bf16_f32 v5, v10, v11
	v_add_u32_e32 v8, s46, v34
	ds_read_b32 v10, v52
	ds_read_b32 v11, v52 offset:1028
	ds_read_b32 v12, v52 offset:2056
	ds_read_b32 v13, v52 offset:3084
	ds_read_b32 v14, v52 offset:4112
	ds_read_b32 v15, v52 offset:5140
	ds_read_b32 v16, v52 offset:6168
	ds_read_b32 v17, v52 offset:7196
	s_ashr_i32 s45, s44, 31
	v_ashrrev_i32_e32 v9, 31, v8
	v_lshl_add_u64 v[6:7], s[44:45], 1, v[38:39]
	v_lshlrev_b64 v[8:9], 13, v[8:9]
	v_lshl_add_u64 v[8:9], v[6:7], 0, v[8:9]
	global_store_dwordx4 v[8:9], v[2:5], off
	v_add_u32_e32 v8, s46, v51
	v_ashrrev_i32_e32 v9, 31, v8
	s_waitcnt lgkmcnt(6)
	v_cvt_pk_bf16_f32 v2, v10, v11
	s_waitcnt lgkmcnt(4)
	v_cvt_pk_bf16_f32 v3, v12, v13
	s_waitcnt lgkmcnt(2)
	v_cvt_pk_bf16_f32 v4, v14, v15
	s_waitcnt lgkmcnt(0)
	v_cvt_pk_bf16_f32 v5, v16, v17
	ds_read_b32 v10, v54
	ds_read_b32 v11, v54 offset:1028
	ds_read_b32 v12, v54 offset:2056
	ds_read_b32 v13, v54 offset:3084
	ds_read_b32 v14, v54 offset:4112
	ds_read_b32 v15, v54 offset:5140
	ds_read_b32 v16, v54 offset:6168
	ds_read_b32 v17, v54 offset:7196
	v_lshlrev_b64 v[8:9], 13, v[8:9]
	v_lshl_add_u64 v[8:9], v[6:7], 0, v[8:9]
	global_store_dwordx4 v[8:9], v[2:5], off
	v_add_u32_e32 v8, s46, v53
	v_ashrrev_i32_e32 v9, 31, v8
	s_waitcnt lgkmcnt(6)
	v_cvt_pk_bf16_f32 v2, v10, v11
	s_waitcnt lgkmcnt(4)
	v_cvt_pk_bf16_f32 v3, v12, v13
	s_waitcnt lgkmcnt(2)
	v_cvt_pk_bf16_f32 v4, v14, v15
	s_waitcnt lgkmcnt(0)
	v_cvt_pk_bf16_f32 v5, v16, v17
	v_lshlrev_b64 v[8:9], 13, v[8:9]
	ds_read_b32 v10, v56
	ds_read_b32 v11, v56 offset:1028
	ds_read_b32 v12, v56 offset:2056
	ds_read_b32 v13, v56 offset:3084
	ds_read_b32 v14, v56 offset:4112
	ds_read_b32 v15, v56 offset:5140
	ds_read_b32 v16, v56 offset:6168
	ds_read_b32 v17, v56 offset:7196
	v_lshl_add_u64 v[8:9], v[6:7], 0, v[8:9]
	global_store_dwordx4 v[8:9], v[2:5], off
	v_add_u32_e32 v8, s46, v55
	v_ashrrev_i32_e32 v9, 31, v8
	v_lshlrev_b64 v[8:9], 13, v[8:9]
	s_add_i32 s49, s49, s18
	s_add_i32 s48, s48, s64
	s_waitcnt lgkmcnt(6)
	v_cvt_pk_bf16_f32 v2, v10, v11
	s_waitcnt lgkmcnt(4)
	v_cvt_pk_bf16_f32 v3, v12, v13
	s_waitcnt lgkmcnt(2)
	v_cvt_pk_bf16_f32 v4, v14, v15
	s_waitcnt lgkmcnt(0)
	v_cvt_pk_bf16_f32 v5, v16, v17
	v_lshl_add_u64 v[6:7], v[6:7], 0, v[8:9]
	s_cmpk_lt_i32 s49, 0x400
	global_store_dwordx4 v[6:7], v[2:5], off
	s_cbranch_scc0 .LBB0_46

;     ...
;     __syncthreads();
; #pragma unroll
;     for (int i = 0; i < 8; ++i) {
;       const int id = tid + i * 512;
;       const int r = id >> 6, c4 = (id & 63) * 4;
;       tile[r * 257 + c4 + 0] = v[i][0];
;       tile[r * 257 + c4 + 1] = v[i][1];
;       tile[r * 257 + c4 + 2] = v[i][2];
;       tile[r * 257 + c4 + 3] = v[i][3];
;     }
;     __syncthreads();
; #pragma unroll
;     for (int i = 0; i < 4; ++i) {
;       const int id = tid + i * 512;
;       const int n = id >> 3, kc = id & 7;
;       uint4 o;
;       o.x = pack2(tile[(kc * 8 + 0) * 257 + n], tile[(kc * 8 + 1) * 257 + n]);
;       o.y = pack2(tile[(kc * 8 + 2) * 257 + n], tile[(kc * 8 + 3) * 257 + n]);
;       o.z = pack2(tile[(kc * 8 + 4) * 257 + n], tile[(kc * 8 + 5) * 257 + n]);
;       o.w = pack2(tile[(kc * 8 + 6) * 257 + n], tile[(kc * 8 + 7) * 257 + n]);
;       *(uint4*)(dst + (size_t)(n0 + n) * K + k0 + kc * 8) = o;
;     }
.LBB0_50:
	s_or_b64 exec, exec, s[46:47]
	s_barrier
	s_waitcnt vmcnt(7)
	ds_write2_b32 v57, v6, v7 offset1:1
	ds_write2_b32 v57, v8, v9 offset0:2 offset1:3
	s_waitcnt vmcnt(6)
	ds_write2_b32 v58, v2, v3 offset1:1
	ds_write2_b32 v58, v4, v5 offset0:2 offset1:3
	s_waitcnt vmcnt(5)
	ds_write2_b32 v59, v14, v15 offset1:1
	ds_write2_b32 v59, v16, v17 offset0:2 offset1:3
	s_waitcnt vmcnt(4)
	ds_write2_b32 v60, v10, v11 offset1:1
	ds_write2_b32 v60, v12, v13 offset0:2 offset1:3
	s_waitcnt vmcnt(3)
	ds_write2_b32 v61, v22, v23 offset1:1
	ds_write2_b32 v61, v24, v25 offset0:2 offset1:3
	s_waitcnt vmcnt(2)
	ds_write2_b32 v62, v18, v19 offset1:1
	ds_write2_b32 v62, v20, v21 offset0:2 offset1:3
	s_waitcnt vmcnt(1)
	ds_write2_b32 v63, v30, v31 offset1:1
	ds_write2_b32 v63, v32, v33 offset0:2 offset1:3
	s_waitcnt vmcnt(0)
	ds_write2_b32 v64, v26, v27 offset1:1
	ds_write2_b32 v64, v28, v29 offset0:2 offset1:3
	s_waitcnt lgkmcnt(0)
	s_barrier
	ds_read_b32 v2, v42
	ds_read_b32 v3, v42 offset:1028
	ds_read_b32 v4, v42 offset:2056
	ds_read_b32 v5, v42 offset:3084
	ds_read_b32 v8, v42 offset:4112
	ds_read_b32 v9, v42 offset:5140
	ds_read_b32 v10, v42 offset:6168
	ds_read_b32 v11, v42 offset:7196
	s_waitcnt lgkmcnt(6)
	v_cvt_pk_bf16_f32 v2, v2, v3
	s_waitcnt lgkmcnt(4)
	v_cvt_pk_bf16_f32 v3, v4, v5
	s_waitcnt lgkmcnt(2)
	v_cvt_pk_bf16_f32 v4, v8, v9
	v_add_u32_e32 v8, s8, v34
	s_waitcnt lgkmcnt(0)
	v_cvt_pk_bf16_f32 v5, v10, v11
	ds_read_b32 v10, v52
	ds_read_b32 v11, v52 offset:1028
	ds_read_b32 v12, v52 offset:2056
	ds_read_b32 v13, v52 offset:3084
	ds_read_b32 v14, v52 offset:4112
	ds_read_b32 v15, v52 offset:5140
	ds_read_b32 v16, v52 offset:6168
	ds_read_b32 v17, v52 offset:7196
	s_ashr_i32 s45, s44, 31
	v_ashrrev_i32_e32 v9, 31, v8
	v_lshl_add_u64 v[6:7], s[44:45], 1, v[38:39]
	v_lshlrev_b64 v[8:9], 13, v[8:9]
	v_lshl_add_u64 v[8:9], v[6:7], 0, v[8:9]
	global_store_dwordx4 v[8:9], v[2:5], off
	v_add_u32_e32 v8, s8, v51
	v_ashrrev_i32_e32 v9, 31, v8
	s_waitcnt lgkmcnt(6)
	v_cvt_pk_bf16_f32 v2, v10, v11
	s_waitcnt lgkmcnt(4)
	v_cvt_pk_bf16_f32 v3, v12, v13
	s_waitcnt lgkmcnt(2)
	v_cvt_pk_bf16_f32 v4, v14, v15
	s_waitcnt lgkmcnt(0)
	v_cvt_pk_bf16_f32 v5, v16, v17
	ds_read_b32 v10, v54
	ds_read_b32 v11, v54 offset:1028
	ds_read_b32 v12, v54 offset:2056
	ds_read_b32 v13, v54 offset:3084
	ds_read_b32 v14, v54 offset:4112
	ds_read_b32 v15, v54 offset:5140
	ds_read_b32 v16, v54 offset:6168
	ds_read_b32 v17, v54 offset:7196
	v_lshlrev_b64 v[8:9], 13, v[8:9]
	v_lshl_add_u64 v[8:9], v[6:7], 0, v[8:9]
	global_store_dwordx4 v[8:9], v[2:5], off
	v_add_u32_e32 v8, s8, v53
	v_ashrrev_i32_e32 v9, 31, v8
	s_waitcnt lgkmcnt(6)
	v_cvt_pk_bf16_f32 v2, v10, v11
	s_waitcnt lgkmcnt(4)
	v_cvt_pk_bf16_f32 v3, v12, v13
	s_waitcnt lgkmcnt(2)
	v_cvt_pk_bf16_f32 v4, v14, v15
	s_waitcnt lgkmcnt(0)
	v_cvt_pk_bf16_f32 v5, v16, v17
	v_lshlrev_b64 v[8:9], 13, v[8:9]
	ds_read_b32 v10, v56
	ds_read_b32 v11, v56 offset:1028
	ds_read_b32 v12, v56 offset:2056
	ds_read_b32 v13, v56 offset:3084
	ds_read_b32 v14, v56 offset:4112
	ds_read_b32 v15, v56 offset:5140
	ds_read_b32 v16, v56 offset:6168
	ds_read_b32 v17, v56 offset:7196
	v_lshl_add_u64 v[8:9], v[6:7], 0, v[8:9]
	global_store_dwordx4 v[8:9], v[2:5], off
	v_add_u32_e32 v8, s8, v55
	v_ashrrev_i32_e32 v9, 31, v8
	v_lshlrev_b64 v[8:9], 13, v[8:9]
	s_add_i32 s48, s48, s18
	s_add_i32 s49, s49, s64
	s_waitcnt lgkmcnt(6)
	v_cvt_pk_bf16_f32 v2, v10, v11
	s_waitcnt lgkmcnt(4)
	v_cvt_pk_bf16_f32 v3, v12, v13
	s_waitcnt lgkmcnt(2)
	v_cvt_pk_bf16_f32 v4, v14, v15
	s_waitcnt lgkmcnt(0)
	v_cvt_pk_bf16_f32 v5, v16, v17
	v_lshl_add_u64 v[6:7], v[6:7], 0, v[8:9]
	s_cmpk_lt_i32 s48, 0xf40
	global_store_dwordx4 v[6:7], v[2:5], off
	s_cbranch_scc0 .LBB0_67

;     ...
;     __syncthreads();
; #pragma unroll
;     for (int i = 0; i < 8; ++i) {
;       const int id = tid + i * 512;
;       const int r = id >> 6, c4 = (id & 63) * 4;
;       tile[r * 257 + c4 + 0] = v[i][0];
;       tile[r * 257 + c4 + 1] = v[i][1];
;       tile[r * 257 + c4 + 2] = v[i][2];
;       tile[r * 257 + c4 + 3] = v[i][3];
;     }
;     __syncthreads();
; #pragma unroll
;     for (int i = 0; i < 4; ++i) {
;       const int id = tid + i * 512;
;       const int n = id >> 3, kc = id & 7;
;       uint4 o;
;       o.x = pack2(tile[(kc * 8 + 0) * 257 + n], tile[(kc * 8 + 1) * 257 + n]);
;       o.y = pack2(tile[(kc * 8 + 2) * 257 + n], tile[(kc * 8 + 3) * 257 + n]);
;       o.z = pack2(tile[(kc * 8 + 4) * 257 + n], tile[(kc * 8 + 5) * 257 + n]);
;       o.w = pack2(tile[(kc * 8 + 6) * 257 + n], tile[(kc * 8 + 7) * 257 + n]);
;       *(uint4*)(dst + (size_t)(n0 + n) * K + k0 + kc * 8) = o;
;     }
.LBB0_142:
	s_or_b64 exec, exec, s[12:13]
	s_barrier
	s_waitcnt vmcnt(7)
	ds_write2_b32 v55, v0, v1 offset1:1
	ds_write2_b32 v55, v2, v3 offset0:2 offset1:3
	s_waitcnt vmcnt(6)
	ds_write2_b32 v56, v8, v9 offset1:1
	ds_write2_b32 v56, v10, v11 offset0:2 offset1:3
	s_waitcnt vmcnt(5)
	ds_write2_b32 v57, v4, v5 offset1:1
	ds_write2_b32 v57, v6, v7 offset0:2 offset1:3
	s_waitcnt vmcnt(4)
	ds_write2_b32 v58, v16, v17 offset1:1
	ds_write2_b32 v58, v18, v19 offset0:2 offset1:3
	s_waitcnt vmcnt(3)
	ds_write2_b32 v59, v12, v13 offset1:1
	ds_write2_b32 v59, v14, v15 offset0:2 offset1:3
	s_waitcnt vmcnt(2)
	ds_write2_b32 v60, v24, v25 offset1:1
	ds_write2_b32 v60, v26, v27 offset0:2 offset1:3
	s_waitcnt vmcnt(1)
	ds_write2_b32 v61, v20, v21 offset1:1
	ds_write2_b32 v61, v22, v23 offset0:2 offset1:3
	s_waitcnt vmcnt(0)
	ds_write2_b32 v62, v28, v29 offset1:1
	ds_write2_b32 v62, v30, v31 offset0:2 offset1:3
	s_waitcnt lgkmcnt(0)
	s_barrier
	ds_read_b32 v0, v40
	ds_read_b32 v1, v40 offset:1028
	ds_read_b32 v2, v40 offset:2056
	ds_read_b32 v3, v40 offset:3084
	ds_read_b32 v6, v40 offset:4112
	ds_read_b32 v7, v40 offset:5140
	ds_read_b32 v8, v40 offset:6168
	ds_read_b32 v9, v40 offset:7196
	s_waitcnt lgkmcnt(6)
	v_cvt_pk_bf16_f32 v0, v0, v1
	s_waitcnt lgkmcnt(4)
	v_cvt_pk_bf16_f32 v1, v2, v3
	s_waitcnt lgkmcnt(2)
	v_cvt_pk_bf16_f32 v2, v6, v7
	v_add_u32_e32 v6, s8, v39
	s_waitcnt lgkmcnt(0)
	v_cvt_pk_bf16_f32 v3, v8, v9
	ds_read_b32 v8, v50
	ds_read_b32 v9, v50 offset:1028
	ds_read_b32 v10, v50 offset:2056
	ds_read_b32 v11, v50 offset:3084
	ds_read_b32 v12, v50 offset:4112
	ds_read_b32 v13, v50 offset:5140
	ds_read_b32 v14, v50 offset:6168
	ds_read_b32 v15, v50 offset:7196
	s_ashr_i32 s11, s10, 31
	v_ashrrev_i32_e32 v7, 31, v6
	v_lshl_add_u64 v[4:5], s[10:11], 1, v[34:35]
	v_lshlrev_b64 v[6:7], 13, v[6:7]
	v_lshl_add_u64 v[6:7], v[4:5], 0, v[6:7]
	global_store_dwordx4 v[6:7], v[0:3], off
	v_add_u32_e32 v6, s8, v49
	v_ashrrev_i32_e32 v7, 31, v6
	s_waitcnt lgkmcnt(6)
	v_cvt_pk_bf16_f32 v0, v8, v9
	s_waitcnt lgkmcnt(4)
	v_cvt_pk_bf16_f32 v1, v10, v11
	s_waitcnt lgkmcnt(2)
	v_cvt_pk_bf16_f32 v2, v12, v13
	s_waitcnt lgkmcnt(0)
	v_cvt_pk_bf16_f32 v3, v14, v15
	ds_read_b32 v8, v52
	ds_read_b32 v9, v52 offset:1028
	ds_read_b32 v10, v52 offset:2056
	ds_read_b32 v11, v52 offset:3084
	ds_read_b32 v12, v52 offset:4112
	ds_read_b32 v13, v52 offset:5140
	ds_read_b32 v14, v52 offset:6168
	ds_read_b32 v15, v52 offset:7196
	v_lshlrev_b64 v[6:7], 13, v[6:7]
	v_lshl_add_u64 v[6:7], v[4:5], 0, v[6:7]
	global_store_dwordx4 v[6:7], v[0:3], off
	v_add_u32_e32 v6, s8, v51
	v_ashrrev_i32_e32 v7, 31, v6
	s_waitcnt lgkmcnt(6)
	v_cvt_pk_bf16_f32 v0, v8, v9
	s_waitcnt lgkmcnt(4)
	v_cvt_pk_bf16_f32 v1, v10, v11
	s_waitcnt lgkmcnt(2)
	v_cvt_pk_bf16_f32 v2, v12, v13
	s_waitcnt lgkmcnt(0)
	v_cvt_pk_bf16_f32 v3, v14, v15
	v_lshlrev_b64 v[6:7], 13, v[6:7]
	ds_read_b32 v8, v54
	ds_read_b32 v9, v54 offset:1028
	ds_read_b32 v10, v54 offset:2056
	ds_read_b32 v11, v54 offset:3084
	ds_read_b32 v12, v54 offset:4112
	ds_read_b32 v13, v54 offset:5140
	ds_read_b32 v14, v54 offset:6168
	ds_read_b32 v15, v54 offset:7196
	v_lshl_add_u64 v[6:7], v[4:5], 0, v[6:7]
	global_store_dwordx4 v[6:7], v[0:3], off
	v_add_u32_e32 v6, s8, v53
	v_ashrrev_i32_e32 v7, 31, v6
	v_lshlrev_b64 v[6:7], 13, v[6:7]
	s_add_i32 s14, s14, s15
	s_add_i32 s16, s16, s17
	s_waitcnt lgkmcnt(6)
	v_cvt_pk_bf16_f32 v0, v8, v9
	s_waitcnt lgkmcnt(4)
	v_cvt_pk_bf16_f32 v1, v10, v11
	s_waitcnt lgkmcnt(2)
	v_cvt_pk_bf16_f32 v2, v12, v13
	s_waitcnt lgkmcnt(0)
	v_cvt_pk_bf16_f32 v3, v14, v15
	v_lshl_add_u64 v[4:5], v[4:5], 0, v[6:7]
	s_cmpk_lt_i32 s14, 0x780
	global_store_dwordx4 v[4:5], v[0:3], off
	s_cbranch_scc0 .LBB0_159

;     ...
;     __syncthreads();
; #pragma unroll
;     for (int i = 0; i < 8; ++i) {
;       const int id = tid + i * 512;
;       const int r = id >> 6, c4 = (id & 63) * 4;
;       tile[r * 257 + c4 + 0] = v[i][0];
;       tile[r * 257 + c4 + 1] = v[i][1];
;       tile[r * 257 + c4 + 2] = v[i][2];
;       tile[r * 257 + c4 + 3] = v[i][3];
;     }
;     __syncthreads();
; #pragma unroll
;     for (int i = 0; i < 4; ++i) {
;       const int id = tid + i * 512;
;       const int n = id >> 3, kc = id & 7;
;       uint4 o;
;       o.x = pack2(tile[(kc * 8 + 0) * 257 + n], tile[(kc * 8 + 1) * 257 + n]);
;       o.y = pack2(tile[(kc * 8 + 2) * 257 + n], tile[(kc * 8 + 3) * 257 + n]);
;       o.z = pack2(tile[(kc * 8 + 4) * 257 + n], tile[(kc * 8 + 5) * 257 + n]);
;       o.w = pack2(tile[(kc * 8 + 6) * 257 + n], tile[(kc * 8 + 7) * 257 + n]);
;       *(uint4*)(dst + (size_t)(n0 + n) * K + k0 + kc * 8) = o;
;     }
.Lwo_29:
	s_or_b64 exec, exec, s[46:47]
	s_barrier
	s_waitcnt vmcnt(7)
	ds_write2_b32 v57, v6, v7 offset1:1
	ds_write2_b32 v57, v8, v9 offset0:2 offset1:3
	s_waitcnt vmcnt(6)
	ds_write2_b32 v58, v2, v3 offset1:1
	ds_write2_b32 v58, v4, v5 offset0:2 offset1:3
	s_waitcnt vmcnt(5)
	ds_write2_b32 v59, v14, v15 offset1:1
	ds_write2_b32 v59, v16, v17 offset0:2 offset1:3
	s_waitcnt vmcnt(4)
	ds_write2_b32 v60, v10, v11 offset1:1
	ds_write2_b32 v60, v12, v13 offset0:2 offset1:3
	s_waitcnt vmcnt(3)
	ds_write2_b32 v61, v22, v23 offset1:1
	ds_write2_b32 v61, v24, v25 offset0:2 offset1:3
	s_waitcnt vmcnt(2)
	ds_write2_b32 v62, v18, v19 offset1:1
	ds_write2_b32 v62, v20, v21 offset0:2 offset1:3
	s_waitcnt vmcnt(1)
	ds_write2_b32 v63, v30, v31 offset1:1
	ds_write2_b32 v63, v32, v33 offset0:2 offset1:3
	s_waitcnt vmcnt(0)
	ds_write2_b32 v64, v26, v27 offset1:1
	ds_write2_b32 v64, v28, v29 offset0:2 offset1:3
	s_waitcnt lgkmcnt(0)
	s_barrier
	ds_read_b32 v2, v42
	ds_read_b32 v3, v42 offset:1028
	ds_read_b32 v4, v42 offset:2056
	ds_read_b32 v5, v42 offset:3084
	ds_read_b32 v8, v42 offset:4112
	ds_read_b32 v9, v42 offset:5140
	ds_read_b32 v10, v42 offset:6168
	ds_read_b32 v11, v42 offset:7196
	s_sub_i32 s46, 0, s45
	s_add_i32 s46, s46, s48
	s_waitcnt lgkmcnt(6)
	v_cvt_pk_bf16_f32 v2, v2, v3
	s_waitcnt lgkmcnt(4)
	v_cvt_pk_bf16_f32 v3, v4, v5
	s_waitcnt lgkmcnt(2)
	v_cvt_pk_bf16_f32 v4, v8, v9
	s_waitcnt lgkmcnt(0)
	v_cvt_pk_bf16_f32 v5, v10, v11
	v_add_u32_e32 v8, s46, v34
	ds_read_b32 v10, v52
	ds_read_b32 v11, v52 offset:1028
	ds_read_b32 v12, v52 offset:2056
	ds_read_b32 v13, v52 offset:3084
	ds_read_b32 v14, v52 offset:4112
	ds_read_b32 v15, v52 offset:5140
	ds_read_b32 v16, v52 offset:6168
	ds_read_b32 v17, v52 offset:7196
	s_ashr_i32 s45, s44, 31
	v_ashrrev_i32_e32 v9, 31, v8
	v_lshl_add_u64 v[6:7], s[44:45], 1, v[38:39]
	v_lshlrev_b64 v[8:9], 13, v[8:9]
	v_lshl_add_u64 v[8:9], v[6:7], 0, v[8:9]
	global_store_dwordx4 v[8:9], v[2:5], off
	v_add_u32_e32 v8, s46, v51
	v_ashrrev_i32_e32 v9, 31, v8
	s_waitcnt lgkmcnt(6)
	v_cvt_pk_bf16_f32 v2, v10, v11
	s_waitcnt lgkmcnt(4)
	v_cvt_pk_bf16_f32 v3, v12, v13
	s_waitcnt lgkmcnt(2)
	v_cvt_pk_bf16_f32 v4, v14, v15
	s_waitcnt lgkmcnt(0)
	v_cvt_pk_bf16_f32 v5, v16, v17
	ds_read_b32 v10, v54
	ds_read_b32 v11, v54 offset:1028
	ds_read_b32 v12, v54 offset:2056
	ds_read_b32 v13, v54 offset:3084
	ds_read_b32 v14, v54 offset:4112
	ds_read_b32 v15, v54 offset:5140
	ds_read_b32 v16, v54 offset:6168
	ds_read_b32 v17, v54 offset:7196
	v_lshlrev_b64 v[8:9], 13, v[8:9]
	v_lshl_add_u64 v[8:9], v[6:7], 0, v[8:9]
	global_store_dwordx4 v[8:9], v[2:5], off
	v_add_u32_e32 v8, s46, v53
	v_ashrrev_i32_e32 v9, 31, v8
	s_waitcnt lgkmcnt(6)
	v_cvt_pk_bf16_f32 v2, v10, v11
	s_waitcnt lgkmcnt(4)
	v_cvt_pk_bf16_f32 v3, v12, v13
	s_waitcnt lgkmcnt(2)
	v_cvt_pk_bf16_f32 v4, v14, v15
	s_waitcnt lgkmcnt(0)
	v_cvt_pk_bf16_f32 v5, v16, v17
	v_lshlrev_b64 v[8:9], 13, v[8:9]
	ds_read_b32 v10, v56
	ds_read_b32 v11, v56 offset:1028
	ds_read_b32 v12, v56 offset:2056
	ds_read_b32 v13, v56 offset:3084
	ds_read_b32 v14, v56 offset:4112
	ds_read_b32 v15, v56 offset:5140
	ds_read_b32 v16, v56 offset:6168
	ds_read_b32 v17, v56 offset:7196
	v_lshl_add_u64 v[8:9], v[6:7], 0, v[8:9]
	global_store_dwordx4 v[8:9], v[2:5], off
	v_add_u32_e32 v8, s46, v55
	v_ashrrev_i32_e32 v9, 31, v8
	v_lshlrev_b64 v[8:9], 13, v[8:9]
	s_add_i32 s49, s49, s99
	s_add_i32 s48, s48, s100
	s_waitcnt lgkmcnt(6)
	v_cvt_pk_bf16_f32 v2, v10, v11
	s_waitcnt lgkmcnt(4)
	v_cvt_pk_bf16_f32 v3, v12, v13
	s_waitcnt lgkmcnt(2)
	v_cvt_pk_bf16_f32 v4, v14, v15
	s_waitcnt lgkmcnt(0)
	v_cvt_pk_bf16_f32 v5, v16, v17
	v_lshl_add_u64 v[6:7], v[6:7], 0, v[8:9]
	s_cmpk_lt_i32 s49, 0x400
	global_store_dwordx4 v[6:7], v[2:5], off
	s_cbranch_scc0 .Lwo_done
